# v96: P1 epilogue - 4 of each unit's stores parked in v232-255 and issued one per super-phase in the next unit's first K iteration
# speedup vs baseline: 1.0032x; 1.0032x over previous
.LBB0_182:
	v_lshlrev_b32_e32 v13, 1, v12
	v_lshlrev_b32_e32 v15, 2, v139
	s_lshl_b32 s69, s16, 6
	v_lshl_or_b32 v14, v139, 6, v13
	s_lshl_b32 s16, s16, 13
	v_and_b32_e32 v15, 32, v15
	v_bitop3_b32 v14, v14, s16, v15 bitop3:0xde
	s_mov_b64 s[16:17], 0x80
	s_sext_i32_i16 s94, s6
	s_and_b32 s6, s7, 3
	s_add_i32 m0, s64, 0x18000
	v_lshl_add_u64 v[6:7], v[6:7], 0, s[16:17]
	s_lshl_b32 s24, s6, 5
	s_lshl_b32 s22, s6, 12
	s_waitcnt vmcnt(2)
	s_barrier
	global_load_lds_dwordx4 v[6:7], off
	v_lshl_add_u64 v[2:3], v[2:3], 0, s[16:17]
	s_add_i32 m0, s64, 0x1a000
	s_add_i32 s70, s64, 0x8000
	s_add_i32 s71, s64, 0xa000
	global_load_lds_dwordx4 v[2:3], off
	v_lshl_add_u64 v[0:1], v[0:1], 0, s[16:17]
	s_mov_b32 m0, s70
	s_add_u32 s20, s56, 0x40080
	global_load_lds_dwordx4 v[0:1], off
	v_lshl_add_u64 v[0:1], v[4:5], 0, s[16:17]
	s_mov_b32 m0, s71
	s_addc_u32 s21, s57, 0
	global_load_lds_dwordx4 v[0:1], off
	s_add_i32 m0, s64, 0x1c000
	v_lshl_add_u64 v[0:1], s[20:21], 0, v[132:133]
	global_load_lds_dwordx4 v[0:1], off
	v_lshl_add_u64 v[0:1], s[20:21], 0, v[128:129]
	s_add_i32 m0, s64, 0x1e000
	v_lshlrev_b32_e32 v15, 6, v158
	global_load_lds_dwordx4 v[0:1], off
	s_movk_i32 s19, 0x3c0
	v_lshlrev_b32_e32 v1, 2, v158
	v_and_or_b32 v0, v15, s19, v13
	v_and_b32_e32 v1, 32, v1
	v_lshlrev_b32_e32 v136, 2, v12
	v_bitop3_b32 v159, s22, v0, v1 bitop3:0xf6
	s_cmpk_lt_u32 s18, 0x100
	v_lshl_add_u64 v[0:1], s[10:11], 0, v[136:137]
	s_mov_b64 s[22:23], 0x500000
	s_cselect_b64 s[18:19], -1, 0
	s_cmp_eq_u32 s6, 0
	v_lshl_add_u64 v[140:141], v[0:1], 0, s[22:23]
	v_and_or_b32 v0, s24, 32, v12
	s_cselect_b64 s[20:21], -1, 0
	s_lshl_b32 s6, s7, 11
	v_lshlrev_b32_e32 v136, 1, v0
	s_and_b32 s72, s6, 0x1000
	v_lshl_add_u64 v[0:1], s[10:11], 0, v[136:137]
	s_mov_b64 s[6:7], 0x2000000
	v_lshl_add_u64 v[142:143], v[0:1], 0, s[6:7]
	v_lshlrev_b32_e32 v0, 15, v72
	v_lshlrev_b32_e32 v1, 11, v11
	v_or3_b32 v0, v9, v0, v1
	v_add_u32_e32 v144, v0, v10
	v_lshlrev_b32_e32 v0, 4, v8
	s_waitcnt vmcnt(6)
	v_and_b32_e32 v0, 0x78000, v0
	v_or3_b32 v0, v9, v0, v1
	s_add_i32 s74, 0, 0x10000
	s_add_i32 s75, 0, 0x14000
	v_or_b32_e32 v138, s24, v12
	s_ashr_i32 s73, s3, 31
	v_mov_b32_e32 v145, v137
	v_add_u32_e32 v146, v0, v10
	v_mov_b32_e32 v147, v137
	v_mov_b64_e32 v[148:149], 0xe00
	v_mov_b64_e32 v[150:151], 0xdff
	v_add_u32_e32 v160, s74, v159
	v_add_u32_e32 v161, s75, v159
	v_add_u32_e32 v162, 0, v14
	s_mov_b32 s76, 0x19ffe000
	s_mov_b32 s77, 0x1a03e000
	s_mov_b32 s78, 0x1a046000
	s_mov_b32 s79, 0x1a04e000
	s_mov_b32 s80, 0x15fff000
	s_mov_b32 s81, 0x1603f000
	s_mov_b32 s82, 0x16047000
	s_mov_b32 s83, 0x1604f000
	s_mov_b64 s[22:23], 0x5fff000
	s_mov_b32 s84, 0x5fff000
	s_mov_b64 s[24:25], 0x603f000
	s_mov_b32 s85, 0x603f000
	s_mov_b64 s[26:27], 0x6047000
	s_mov_b32 s86, 0x6047000
	s_mov_b64 s[28:29], 0x604f000
	s_mov_b32 s87, 0x604f000
	s_mov_b64 s[30:31], 0x6057000
	s_mov_b32 s88, 0x6057000
	s_mov_b32 s89, 0x12000000
	s_mov_b64 s[34:35], 0x20000
	s_mov_b32 s90, 0x20000
	s_mov_b64 s[36:37], 0x24000
	s_mov_b32 s91, 0x24000
	s_mov_b64 s[38:39], 0x28000
	s_mov_b32 s92, 0x28000
	s_mov_b64 s[42:43], 0x2c000
	s_mov_b32 s93, 0x2c000
	v_mov_b32_e32 v163, 0x3db504f3
	s_barrier
	s_waitcnt vmcnt(0)
	s_mov_b32 s100, 1
	s_branch .LBB0_185

.LBB0_188:
	ds_read_b128 v[152:155], v160
	ds_read_b128 v[164:167], v160 offset:1024
	ds_read_b128 v[168:171], v160 offset:2048
	ds_read_b128 v[172:175], v160 offset:3072
	ds_read_b128 v[176:179], v161
	ds_read_b128 v[180:183], v161 offset:1024
	ds_read_b128 v[184:187], v161 offset:2048
	ds_read_b128 v[188:191], v161 offset:3072
	s_add_u32 s56, s54, 0xfffc0080
	s_addc_u32 s57, s55, -1
	s_cmp_eq_u32 s98, 12
	s_cselect_b32 s59, s47, s57
	s_cselect_b32 s58, s53, s56
	s_cselect_b32 s57, s45, s97
	s_cselect_b32 s56, s95, s96
	v_lshl_add_u64 v[156:157], s[54:55], 0, v[144:145]
	s_add_i32 m0, s64, 0xc000
	ds_read_b128 v[192:195], v162
	ds_read_b128 v[196:199], v162 offset:1024
	ds_read_b128 v[200:203], v162 offset:2048
	ds_read_b128 v[204:207], v162 offset:3072
	ds_read_b128 v[208:211], v162 offset:4096
	ds_read_b128 v[212:215], v162 offset:5120
	ds_read_b128 v[216:219], v162 offset:6144
	ds_read_b128 v[220:223], v162 offset:7168
	global_load_lds_dwordx4 v[156:157], off
	v_lshl_add_u64 v[156:157], s[54:55], 0, v[146:147]
	s_add_i32 m0, s64, 0xe000
	s_nop 0
	global_load_lds_dwordx4 v[156:157], off
	s_waitcnt vmcnt(8)
	s_waitcnt lgkmcnt(0)
	s_barrier
	s_setprio 1
	s_waitcnt lgkmcnt(0)
	v_mfma_f32_16x16x32_bf16 v[124:127], v[152:155], v[192:195], v[124:127]
	v_mfma_f32_16x16x32_bf16 v[120:123], v[168:171], v[192:195], v[120:123]
	v_mfma_f32_16x16x32_bf16 v[116:119], v[152:155], v[200:203], v[116:119]
	v_mfma_f32_16x16x32_bf16 v[112:115], v[168:171], v[200:203], v[112:115]
	v_mfma_f32_16x16x32_bf16 v[100:103], v[152:155], v[208:211], v[100:103]
	v_mfma_f32_16x16x32_bf16 v[96:99], v[168:171], v[208:211], v[96:99]
	v_mfma_f32_16x16x32_bf16 v[84:87], v[152:155], v[216:219], v[84:87]
	v_mfma_f32_16x16x32_bf16 v[80:83], v[168:171], v[216:219], v[80:83]
	v_mfma_f32_16x16x32_bf16 v[124:127], v[164:167], v[196:199], v[124:127]
	v_mfma_f32_16x16x32_bf16 v[120:123], v[172:175], v[196:199], v[120:123]
	v_mfma_f32_16x16x32_bf16 v[116:119], v[164:167], v[204:207], v[116:119]
	v_mfma_f32_16x16x32_bf16 v[112:115], v[172:175], v[204:207], v[112:115]
	v_mfma_f32_16x16x32_bf16 v[100:103], v[164:167], v[212:215], v[100:103]
	v_mfma_f32_16x16x32_bf16 v[96:99], v[172:175], v[212:215], v[96:99]
	v_mfma_f32_16x16x32_bf16 v[84:87], v[164:167], v[220:223], v[84:87]
	v_mfma_f32_16x16x32_bf16 v[80:83], v[172:175], v[220:223], v[80:83]
	s_setprio 0
	s_setprio 1
	v_mfma_f32_16x16x32_bf16 v[108:111], v[176:179], v[192:195], v[108:111]
	v_mfma_f32_16x16x32_bf16 v[104:107], v[184:187], v[192:195], v[104:107]
	v_mfma_f32_16x16x32_bf16 v[92:95], v[176:179], v[200:203], v[92:95]
	v_mfma_f32_16x16x32_bf16 v[88:91], v[184:187], v[200:203], v[88:91]
	v_mfma_f32_16x16x32_bf16 v[76:79], v[176:179], v[208:211], v[76:79]
	v_mfma_f32_16x16x32_bf16 v[72:75], v[184:187], v[208:211], v[72:75]
	v_mfma_f32_16x16x32_bf16 v[68:71], v[176:179], v[216:219], v[68:71]
	v_mfma_f32_16x16x32_bf16 v[64:67], v[184:187], v[216:219], v[64:67]
	v_mfma_f32_16x16x32_bf16 v[108:111], v[180:183], v[196:199], v[108:111]
	v_mfma_f32_16x16x32_bf16 v[104:107], v[188:191], v[196:199], v[104:107]
	v_mfma_f32_16x16x32_bf16 v[92:95], v[180:183], v[204:207], v[92:95]
	v_mfma_f32_16x16x32_bf16 v[88:91], v[188:191], v[204:207], v[88:91]
	v_mfma_f32_16x16x32_bf16 v[76:79], v[180:183], v[212:215], v[76:79]
	v_mfma_f32_16x16x32_bf16 v[72:75], v[188:191], v[212:215], v[72:75]
	v_mfma_f32_16x16x32_bf16 v[68:71], v[180:183], v[220:223], v[68:71]
	v_mfma_f32_16x16x32_bf16 v[64:67], v[188:191], v[220:223], v[64:67]
	s_setprio 0
	s_barrier
	s_or_b32 s101, s98, s100
	s_cbranch_scc1 .Ldf_skip0
	global_store_dwordx4 v[236:237], v[232:235], off nt
.Ldf_skip0:
	s_add_i32 s99, s74, s33
	v_lshl_add_u64 v[156:157], s[56:57], 0, v[132:133]
	s_mov_b32 m0, s99
	ds_read_b128 v[192:195], v162 offset:16384
	ds_read_b128 v[196:199], v162 offset:17408
	ds_read_b128 v[200:203], v162 offset:18432
	ds_read_b128 v[204:207], v162 offset:19456
	ds_read_b128 v[208:211], v162 offset:20480
	ds_read_b128 v[212:215], v162 offset:21504
	ds_read_b128 v[216:219], v162 offset:22528
	ds_read_b128 v[220:223], v162 offset:23552
	global_load_lds_dwordx4 v[156:157], off
	s_add_i32 m0, s99, 0x2000
	s_add_u32 vcc_lo, s56, 0x40000
	v_lshl_add_u64 v[224:225], s[56:57], 0, v[128:129]
	s_addc_u32 vcc_hi, s57, 0
	s_add_i32 s99, s75, s33
	global_load_lds_dwordx4 v[224:225], off
	v_lshl_add_u64 v[226:227], vcc, 0, v[132:133]
	s_mov_b32 m0, s99
	v_lshl_add_u64 v[228:229], s[58:59], 0, v[130:131]
	global_load_lds_dwordx4 v[226:227], off
	v_lshl_add_u64 v[226:227], vcc, 0, v[128:129]
	s_add_i32 m0, s99, 0x2000
	s_nop 0
	global_load_lds_dwordx4 v[226:227], off
	v_lshl_add_u64 v[226:227], s[58:59], 0, v[134:135]
	s_mov_b32 m0, s64
	s_nop 0
	global_load_lds_dwordx4 v[226:227], off
	s_mov_b32 m0, s65
	s_nop 0
	global_load_lds_dwordx4 v[228:229], off
	s_waitcnt vmcnt(8)
	s_waitcnt lgkmcnt(0)
	s_barrier
	s_setprio 1
	s_waitcnt lgkmcnt(0)
	v_mfma_f32_16x16x32_bf16 v[60:63], v[152:155], v[192:195], v[60:63]
	v_mfma_f32_16x16x32_bf16 v[56:59], v[168:171], v[192:195], v[56:59]
	v_mfma_f32_16x16x32_bf16 v[52:55], v[152:155], v[200:203], v[52:55]
	v_mfma_f32_16x16x32_bf16 v[48:51], v[168:171], v[200:203], v[48:51]
	v_mfma_f32_16x16x32_bf16 v[36:39], v[152:155], v[208:211], v[36:39]
	v_mfma_f32_16x16x32_bf16 v[32:35], v[168:171], v[208:211], v[32:35]
	v_mfma_f32_16x16x32_bf16 v[20:23], v[152:155], v[216:219], v[20:23]
	v_mfma_f32_16x16x32_bf16 v[16:19], v[168:171], v[216:219], v[16:19]
	v_mfma_f32_16x16x32_bf16 v[60:63], v[164:167], v[196:199], v[60:63]
	v_mfma_f32_16x16x32_bf16 v[56:59], v[172:175], v[196:199], v[56:59]
	v_mfma_f32_16x16x32_bf16 v[52:55], v[164:167], v[204:207], v[52:55]
	v_mfma_f32_16x16x32_bf16 v[48:51], v[172:175], v[204:207], v[48:51]
	v_mfma_f32_16x16x32_bf16 v[36:39], v[164:167], v[212:215], v[36:39]
	v_mfma_f32_16x16x32_bf16 v[32:35], v[172:175], v[212:215], v[32:35]
	v_mfma_f32_16x16x32_bf16 v[20:23], v[164:167], v[220:223], v[20:23]
	v_mfma_f32_16x16x32_bf16 v[16:19], v[172:175], v[220:223], v[16:19]
	s_setprio 0
	s_setprio 1
	v_mfma_f32_16x16x32_bf16 v[44:47], v[176:179], v[192:195], v[44:47]
	v_mfma_f32_16x16x32_bf16 v[40:43], v[184:187], v[192:195], v[40:43]
	v_mfma_f32_16x16x32_bf16 v[28:31], v[176:179], v[200:203], v[28:31]
	v_mfma_f32_16x16x32_bf16 v[24:27], v[184:187], v[200:203], v[24:27]
	v_mfma_f32_16x16x32_bf16 v[12:15], v[176:179], v[208:211], v[12:15]
	v_mfma_f32_16x16x32_bf16 v[8:11], v[184:187], v[208:211], v[8:11]
	v_mfma_f32_16x16x32_bf16 v[4:7], v[176:179], v[216:219], v[4:7]
	v_mfma_f32_16x16x32_bf16 v[0:3], v[184:187], v[216:219], v[0:3]
	v_mfma_f32_16x16x32_bf16 v[44:47], v[180:183], v[196:199], v[44:47]
	v_mfma_f32_16x16x32_bf16 v[40:43], v[188:191], v[196:199], v[40:43]
	v_mfma_f32_16x16x32_bf16 v[28:31], v[180:183], v[204:207], v[28:31]
	v_mfma_f32_16x16x32_bf16 v[24:27], v[188:191], v[204:207], v[24:27]
	v_mfma_f32_16x16x32_bf16 v[12:15], v[180:183], v[212:215], v[12:15]
	v_mfma_f32_16x16x32_bf16 v[8:11], v[188:191], v[212:215], v[8:11]
	v_mfma_f32_16x16x32_bf16 v[4:7], v[180:183], v[220:223], v[4:7]
	v_mfma_f32_16x16x32_bf16 v[0:3], v[188:191], v[220:223], v[0:3]
	s_setprio 0
	s_barrier
	s_or_b32 s101, s98, s100
	s_cbranch_scc1 .Ldf_skip1
	global_store_dwordx4 v[242:243], v[238:241], off nt
.Ldf_skip1:
	s_add_i32 s99, 0, 0x18000
	v_add_u32_e32 v136, s99, v159
	s_add_i32 vcc_lo, 0, 0x1c000
	ds_read_b128 v[152:155], v136
	ds_read_b128 v[164:167], v136 offset:1024
	ds_read_b128 v[168:171], v136 offset:2048
	ds_read_b128 v[172:175], v136 offset:3072
	v_add_u32_e32 v136, vcc_lo, v159
	ds_read_b128 v[176:179], v136
	ds_read_b128 v[180:183], v136 offset:1024
	ds_read_b128 v[184:187], v136 offset:2048
	ds_read_b128 v[188:191], v136 offset:3072
	s_add_u32 s58, s58, 0x40000
	s_addc_u32 s59, s59, 0
	s_mov_b32 m0, s66
	v_lshl_add_u64 v[230:231], s[58:59], 0, v[134:135]
	ds_read_b128 v[192:195], v162 offset:32768
	ds_read_b128 v[196:199], v162 offset:33792
	ds_read_b128 v[200:203], v162 offset:34816
	ds_read_b128 v[204:207], v162 offset:35840
	ds_read_b128 v[208:211], v162 offset:36864
	ds_read_b128 v[212:215], v162 offset:37888
	ds_read_b128 v[216:219], v162 offset:38912
	ds_read_b128 v[220:223], v162 offset:39936
	global_load_lds_dwordx4 v[230:231], off
	v_lshl_add_u64 v[230:231], s[58:59], 0, v[130:131]
	s_mov_b32 m0, s67
	s_nop 0
	global_load_lds_dwordx4 v[230:231], off
	s_waitcnt vmcnt(8)
	s_waitcnt lgkmcnt(0)
	s_barrier
	s_setprio 1
	s_waitcnt lgkmcnt(0)
	v_mfma_f32_16x16x32_bf16 v[124:127], v[152:155], v[192:195], v[124:127]
	v_mfma_f32_16x16x32_bf16 v[120:123], v[168:171], v[192:195], v[120:123]
	v_mfma_f32_16x16x32_bf16 v[116:119], v[152:155], v[200:203], v[116:119]
	v_mfma_f32_16x16x32_bf16 v[112:115], v[168:171], v[200:203], v[112:115]
	v_mfma_f32_16x16x32_bf16 v[100:103], v[152:155], v[208:211], v[100:103]
	v_mfma_f32_16x16x32_bf16 v[96:99], v[168:171], v[208:211], v[96:99]
	v_mfma_f32_16x16x32_bf16 v[84:87], v[152:155], v[216:219], v[84:87]
	v_mfma_f32_16x16x32_bf16 v[80:83], v[168:171], v[216:219], v[80:83]
	v_mfma_f32_16x16x32_bf16 v[124:127], v[164:167], v[196:199], v[124:127]
	v_mfma_f32_16x16x32_bf16 v[120:123], v[172:175], v[196:199], v[120:123]
	v_mfma_f32_16x16x32_bf16 v[116:119], v[164:167], v[204:207], v[116:119]
	v_mfma_f32_16x16x32_bf16 v[112:115], v[172:175], v[204:207], v[112:115]
	v_mfma_f32_16x16x32_bf16 v[100:103], v[164:167], v[212:215], v[100:103]
	v_mfma_f32_16x16x32_bf16 v[96:99], v[172:175], v[212:215], v[96:99]
	v_mfma_f32_16x16x32_bf16 v[84:87], v[164:167], v[220:223], v[84:87]
	v_mfma_f32_16x16x32_bf16 v[80:83], v[172:175], v[220:223], v[80:83]
	s_setprio 0
	s_setprio 1
	v_mfma_f32_16x16x32_bf16 v[108:111], v[176:179], v[192:195], v[108:111]
	v_mfma_f32_16x16x32_bf16 v[104:107], v[184:187], v[192:195], v[104:107]
	v_mfma_f32_16x16x32_bf16 v[92:95], v[176:179], v[200:203], v[92:95]
	v_mfma_f32_16x16x32_bf16 v[88:91], v[184:187], v[200:203], v[88:91]
	v_mfma_f32_16x16x32_bf16 v[76:79], v[176:179], v[208:211], v[76:79]
	v_mfma_f32_16x16x32_bf16 v[72:75], v[184:187], v[208:211], v[72:75]
	v_mfma_f32_16x16x32_bf16 v[68:71], v[176:179], v[216:219], v[68:71]
	v_mfma_f32_16x16x32_bf16 v[64:67], v[184:187], v[216:219], v[64:67]
	v_mfma_f32_16x16x32_bf16 v[108:111], v[180:183], v[196:199], v[108:111]
	v_mfma_f32_16x16x32_bf16 v[104:107], v[188:191], v[196:199], v[104:107]
	v_mfma_f32_16x16x32_bf16 v[92:95], v[180:183], v[204:207], v[92:95]
	v_mfma_f32_16x16x32_bf16 v[88:91], v[188:191], v[204:207], v[88:91]
	v_mfma_f32_16x16x32_bf16 v[76:79], v[180:183], v[212:215], v[76:79]
	v_mfma_f32_16x16x32_bf16 v[72:75], v[188:191], v[212:215], v[72:75]
	v_mfma_f32_16x16x32_bf16 v[68:71], v[180:183], v[220:223], v[68:71]
	v_mfma_f32_16x16x32_bf16 v[64:67], v[188:191], v[220:223], v[64:67]
	s_setprio 0
	s_barrier
	s_or_b32 s101, s98, s100
	s_cbranch_scc1 .Ldf_skip2
	global_store_dwordx4 v[248:249], v[244:247], off nt
.Ldf_skip2:
	s_add_i32 s58, s99, s33
	v_lshl_add_u64 v[156:157], v[156:157], 0, s[16:17]
	s_mov_b32 m0, s58
	ds_read_b128 v[192:195], v162 offset:49152
	ds_read_b128 v[196:199], v162 offset:50176
	ds_read_b128 v[200:203], v162 offset:51200
	ds_read_b128 v[204:207], v162 offset:52224
	ds_read_b128 v[208:211], v162 offset:53248
	ds_read_b128 v[212:215], v162 offset:54272
	ds_read_b128 v[216:219], v162 offset:55296
	ds_read_b128 v[220:223], v162 offset:56320
	global_load_lds_dwordx4 v[156:157], off
	s_add_i32 m0, s58, 0x2000
	s_add_u32 s56, s56, 0x40080
	v_lshl_add_u64 v[156:157], v[224:225], 0, s[16:17]
	s_addc_u32 s57, s57, 0
	s_add_i32 s58, vcc_lo, s33
	global_load_lds_dwordx4 v[156:157], off
	v_lshl_add_u64 v[156:157], s[56:57], 0, v[132:133]
	s_mov_b32 m0, s58
	s_nop 0
	global_load_lds_dwordx4 v[156:157], off
	v_lshl_add_u64 v[156:157], s[56:57], 0, v[128:129]
	s_add_i32 m0, s58, 0x2000
	s_nop 0
	global_load_lds_dwordx4 v[156:157], off
	v_lshl_add_u64 v[156:157], v[226:227], 0, s[16:17]
	s_mov_b32 m0, s70
	s_nop 0
	global_load_lds_dwordx4 v[156:157], off
	v_lshl_add_u64 v[156:157], v[228:229], 0, s[16:17]
	s_mov_b32 m0, s71
	s_nop 0
	global_load_lds_dwordx4 v[156:157], off
	s_waitcnt vmcnt(8)
	s_waitcnt lgkmcnt(0)
	s_barrier
	s_setprio 1
	s_waitcnt lgkmcnt(0)
	v_mfma_f32_16x16x32_bf16 v[60:63], v[152:155], v[192:195], v[60:63]
	v_mfma_f32_16x16x32_bf16 v[56:59], v[168:171], v[192:195], v[56:59]
	v_mfma_f32_16x16x32_bf16 v[52:55], v[152:155], v[200:203], v[52:55]
	v_mfma_f32_16x16x32_bf16 v[48:51], v[168:171], v[200:203], v[48:51]
	v_mfma_f32_16x16x32_bf16 v[36:39], v[152:155], v[208:211], v[36:39]
	v_mfma_f32_16x16x32_bf16 v[32:35], v[168:171], v[208:211], v[32:35]
	v_mfma_f32_16x16x32_bf16 v[20:23], v[152:155], v[216:219], v[20:23]
	v_mfma_f32_16x16x32_bf16 v[16:19], v[168:171], v[216:219], v[16:19]
	v_mfma_f32_16x16x32_bf16 v[60:63], v[164:167], v[196:199], v[60:63]
	v_mfma_f32_16x16x32_bf16 v[56:59], v[172:175], v[196:199], v[56:59]
	v_mfma_f32_16x16x32_bf16 v[52:55], v[164:167], v[204:207], v[52:55]
	v_mfma_f32_16x16x32_bf16 v[48:51], v[172:175], v[204:207], v[48:51]
	v_mfma_f32_16x16x32_bf16 v[36:39], v[164:167], v[212:215], v[36:39]
	v_mfma_f32_16x16x32_bf16 v[32:35], v[172:175], v[212:215], v[32:35]
	v_mfma_f32_16x16x32_bf16 v[20:23], v[164:167], v[220:223], v[20:23]
	v_mfma_f32_16x16x32_bf16 v[16:19], v[172:175], v[220:223], v[16:19]
	s_setprio 0
	s_setprio 1
	v_mfma_f32_16x16x32_bf16 v[44:47], v[176:179], v[192:195], v[44:47]
	v_mfma_f32_16x16x32_bf16 v[40:43], v[184:187], v[192:195], v[40:43]
	v_mfma_f32_16x16x32_bf16 v[28:31], v[176:179], v[200:203], v[28:31]
	v_mfma_f32_16x16x32_bf16 v[24:27], v[184:187], v[200:203], v[24:27]
	v_mfma_f32_16x16x32_bf16 v[12:15], v[176:179], v[208:211], v[12:15]
	v_mfma_f32_16x16x32_bf16 v[8:11], v[184:187], v[208:211], v[8:11]
	v_mfma_f32_16x16x32_bf16 v[4:7], v[176:179], v[216:219], v[4:7]
	v_mfma_f32_16x16x32_bf16 v[0:3], v[184:187], v[216:219], v[0:3]
	v_mfma_f32_16x16x32_bf16 v[44:47], v[180:183], v[196:199], v[44:47]
	v_mfma_f32_16x16x32_bf16 v[40:43], v[188:191], v[196:199], v[40:43]
	v_mfma_f32_16x16x32_bf16 v[28:31], v[180:183], v[204:207], v[28:31]
	v_mfma_f32_16x16x32_bf16 v[24:27], v[188:191], v[204:207], v[24:27]
	v_mfma_f32_16x16x32_bf16 v[12:15], v[180:183], v[212:215], v[12:15]
	v_mfma_f32_16x16x32_bf16 v[8:11], v[188:191], v[212:215], v[8:11]
	v_mfma_f32_16x16x32_bf16 v[4:7], v[180:183], v[220:223], v[4:7]
	v_mfma_f32_16x16x32_bf16 v[0:3], v[188:191], v[220:223], v[0:3]
	s_setprio 0
	s_barrier
	s_or_b32 s101, s98, s100
	s_cbranch_scc1 .Ldf_skip3
	global_store_dwordx4 v[254:255], v[250:253], off nt
.Ldf_skip3:
	s_add_i32 s98, s98, 2
	s_add_u32 s54, s54, 0x100
	s_addc_u32 s55, s55, 0
	s_add_u32 s96, s96, 0x100
	s_addc_u32 s97, s97, 0
	s_cmp_gt_u32 s98, 13
	s_cbranch_scc0 .LBB0_188
	s_and_b64 vcc, exec, s[18:19]
	s_cbranch_vccz .LBB0_191
	s_barrier

.LBB0_194:
	s_cmp_gt_i32 s94, 3
	s_cbranch_scc0 .LBB0_210
	s_cmp_gt_u32 s94, 11
	s_cbranch_scc0 .LBB0_207
	s_cmp_gt_u32 s94, 19
	s_cbranch_scc0 .LBB0_204
	s_cmp_gt_u32 s94, 27
	s_cbranch_scc0 .LBB0_201
	s_mov_b32 s100, 1
	s_andn2_b64 vcc, exec, s[20:21]
	s_cbranch_vccnz .LBB0_200
	v_or_b32_e32 v156, 16, v152
	v_ashrrev_i32_e32 v153, 31, v152
	v_ashrrev_i32_e32 v157, 31, v156
	v_lshlrev_b64 v[154:155], 7, v[152:153]
	v_lshlrev_b64 v[156:157], 7, v[156:157]
	v_lshl_add_u64 v[154:155], v[140:141], 0, v[154:155]
	v_lshl_add_u64 v[156:157], v[140:141], 0, v[156:157]
	global_store_dwordx4 v[154:155], v[124:127], off
	global_store_dwordx4 v[154:155], v[120:123], off offset:16
	global_store_dwordx4 v[156:157], v[116:119], off
	global_store_dwordx4 v[156:157], v[112:115], off offset:16
	v_or_b32_e32 v156, 32, v152
	v_ashrrev_i32_e32 v157, 31, v156
	v_lshlrev_b64 v[156:157], 7, v[156:157]
	v_lshl_add_u64 v[156:157], v[140:141], 0, v[156:157]
	global_store_dwordx4 v[156:157], v[100:103], off
	global_store_dwordx4 v[156:157], v[96:99], off offset:16
	v_or_b32_e32 v156, 48, v152
	v_ashrrev_i32_e32 v157, 31, v156
	v_lshlrev_b64 v[156:157], 7, v[156:157]
	s_movk_i32 s47, 0x4000
	v_lshl_add_u64 v[156:157], v[140:141], 0, v[156:157]
	s_mov_b64 s[52:53], 0x4000
	v_add_co_u32_e32 v164, vcc, s47, v154
	global_store_dwordx4 v[156:157], v[84:87], off
	global_store_dwordx4 v[156:157], v[80:83], off offset:16
	v_lshl_add_u64 v[156:157], v[154:155], 0, s[52:53]
	v_addc_co_u32_e32 v165, vcc, 0, v155, vcc
	s_mov_b64 s[52:53], 0x4800
	global_store_dwordx4 v[164:165], v[60:63], off
	global_store_dwordx4 v[156:157], v[56:59], off offset:16
	v_lshl_add_u64 v[156:157], v[154:155], 0, s[52:53]
	global_store_dwordx4 v[164:165], v[52:55], off offset:2048
	global_store_dwordx4 v[156:157], v[48:51], off offset:16
	s_mov_b64 s[52:53], 0x5000
	v_add_co_u32_e32 v164, vcc, 0x5000, v154
	v_lshl_add_u64 v[156:157], v[154:155], 0, s[52:53]
	s_nop 0
	v_addc_co_u32_e32 v165, vcc, 0, v155, vcc
	s_mov_b64 s[52:53], 0x5800
	global_store_dwordx4 v[164:165], v[36:39], off
	global_store_dwordx4 v[156:157], v[32:35], off offset:16
	v_lshl_add_u64 v[154:155], v[154:155], 0, s[52:53]
	global_store_dwordx4 v[164:165], v[20:23], off offset:2048
	global_store_dwordx4 v[154:155], v[16:19], off offset:16

.LBB0_201:
	s_andn2_b64 vcc, exec, s[52:53]
	s_cbranch_vccnz .LBB0_203
	v_ashrrev_i32_e32 v153, 31, v152
	v_mul_f32_e32 v136, 0xbfb8aa3b, v108
	v_lshlrev_b64 v[154:155], 11, v[152:153]
	v_exp_f32_e32 v153, v136
	v_mul_f32_e32 v136, 0xbfb8aa3b, v109
	v_exp_f32_e32 v157, v136
	s_lshl_b32 s47, s94, 8
	v_add_f32_e32 v153, 1.0, v153
	v_rcp_f32_e32 v156, v153
	v_add_f32_e32 v153, 1.0, v157
	v_mul_f32_e32 v157, 0xbfb8aa3b, v110
	v_exp_f32_e32 v164, v157
	v_mul_f32_e32 v157, 0xbfb8aa3b, v111
	v_exp_f32_e32 v165, v157
	v_rcp_f32_e32 v157, v153
	v_add_f32_e32 v153, 1.0, v164
	v_rcp_f32_e32 v166, v153
	v_add_f32_e32 v153, 1.0, v165
	v_rcp_f32_e32 v167, v153
	v_pk_mul_f32 v[156:157], v[108:109], v[156:157]
	v_mul_f32_e32 v153, 0xbfb8aa3b, v104
	v_pk_mul_f32 v[156:157], v[124:125], v[156:157]
	v_exp_f32_e32 v153, v153
	v_mul_f32_e32 v165, 0xbfb8aa3b, v105
	v_cvt_pk_bf16_f32 v164, v156, v157
	v_pk_mul_f32 v[156:157], v[110:111], v[166:167]
	v_exp_f32_e32 v166, v165
	v_pk_mul_f32 v[156:157], v[126:127], v[156:157]
	v_add_f32_e32 v153, 1.0, v153
	v_cvt_pk_bf16_f32 v165, v156, v157
	v_mul_f32_e32 v157, 0xbfb8aa3b, v106
	v_rcp_f32_e32 v156, v153
	v_add_f32_e32 v153, 1.0, v166
	v_exp_f32_e32 v166, v157
	v_mul_f32_e32 v157, 0xbfb8aa3b, v107
	v_exp_f32_e32 v167, v157
	v_rcp_f32_e32 v157, v153
	v_add_f32_e32 v153, 1.0, v166
	v_rcp_f32_e32 v168, v153
	v_add_f32_e32 v153, 1.0, v167
	v_rcp_f32_e32 v169, v153
	s_add_u32 s52, s10, s47
	v_pk_mul_f32 v[156:157], v[104:105], v[156:157]
	s_addc_u32 s53, s11, 0
	v_pk_mul_f32 v[156:157], v[120:121], v[156:157]
	v_lshl_add_u64 v[154:155], s[52:53], 0, v[154:155]
	v_lshlrev_b32_e32 v136, 1, v138
	v_cvt_pk_bf16_f32 v166, v156, v157
	v_pk_mul_f32 v[156:157], v[106:107], v[168:169]
	v_lshl_add_u64 v[154:155], v[154:155], 0, v[136:137]
	v_pk_mul_f32 v[156:157], v[122:123], v[156:157]
	v_mul_f32_e32 v153, 0xbfb8aa3b, v92
	v_cvt_pk_bf16_f32 v167, v156, v157
	v_add_co_u32_e32 v156, vcc, s76, v154
	v_exp_f32_e32 v153, v153
	s_nop 0
	v_addc_co_u32_e32 v157, vcc, 0, v155, vcc
	global_store_dwordx4 v[156:157], v[164:167], off offset:3072 nt
	v_add_f32_e32 v153, 1.0, v153
	v_or_b32_e32 v156, 16, v152
	v_mul_f32_e32 v164, 0xbfb8aa3b, v93
	v_exp_f32_e32 v165, v164
	v_rcp_f32_e32 v164, v153
	v_ashrrev_i32_e32 v157, 31, v156
	v_lshlrev_b64 v[156:157], 11, v[156:157]
	v_add_f32_e32 v153, 1.0, v165
	v_mul_f32_e32 v165, 0xbfb8aa3b, v94
	v_exp_f32_e32 v166, v165
	v_mul_f32_e32 v165, 0xbfb8aa3b, v95
	v_exp_f32_e32 v167, v165
	v_rcp_f32_e32 v165, v153
	v_add_f32_e32 v153, 1.0, v166
	v_rcp_f32_e32 v166, v153
	v_add_f32_e32 v153, 1.0, v167
	v_rcp_f32_e32 v167, v153
	v_pk_mul_f32 v[164:165], v[92:93], v[164:165]
	v_mul_f32_e32 v153, 0xbfb8aa3b, v88
	v_pk_mul_f32 v[164:165], v[116:117], v[164:165]
	v_exp_f32_e32 v153, v153
	v_cvt_pk_bf16_f32 v164, v164, v165
	v_mul_f32_e32 v165, 0xbfb8aa3b, v89
	v_exp_f32_e32 v168, v165
	v_pk_mul_f32 v[166:167], v[94:95], v[166:167]
	v_add_f32_e32 v153, 1.0, v153
	v_pk_mul_f32 v[166:167], v[118:119], v[166:167]
	v_lshl_add_u64 v[156:157], s[52:53], 0, v[156:157]
	v_cvt_pk_bf16_f32 v165, v166, v167
	v_mul_f32_e32 v167, 0xbfb8aa3b, v90
	v_rcp_f32_e32 v166, v153
	v_add_f32_e32 v153, 1.0, v168
	v_exp_f32_e32 v168, v167
	v_mul_f32_e32 v167, 0xbfb8aa3b, v91
	v_exp_f32_e32 v169, v167
	v_rcp_f32_e32 v167, v153
	v_add_f32_e32 v153, 1.0, v168
	v_rcp_f32_e32 v168, v153
	v_add_f32_e32 v153, 1.0, v169
	v_rcp_f32_e32 v169, v153
	v_lshl_add_u64 v[156:157], v[156:157], 0, v[136:137]
	v_pk_mul_f32 v[166:167], v[88:89], v[166:167]
	v_add_co_u32_e32 v156, vcc, s76, v156
	v_pk_mul_f32 v[168:169], v[90:91], v[168:169]
	v_pk_mul_f32 v[166:167], v[112:113], v[166:167]
	v_pk_mul_f32 v[168:169], v[114:115], v[168:169]
	v_cvt_pk_bf16_f32 v166, v166, v167
	v_cvt_pk_bf16_f32 v167, v168, v169
	v_addc_co_u32_e32 v157, vcc, 0, v157, vcc
	v_mul_f32_e32 v153, 0xbfb8aa3b, v76
	global_store_dwordx4 v[156:157], v[164:167], off offset:3072 nt
	v_exp_f32_e32 v153, v153
	v_or_b32_e32 v156, 32, v152
	v_mul_f32_e32 v164, 0xbfb8aa3b, v77
	v_exp_f32_e32 v165, v164
	v_add_f32_e32 v153, 1.0, v153
	v_rcp_f32_e32 v164, v153
	v_ashrrev_i32_e32 v157, 31, v156
	v_add_f32_e32 v153, 1.0, v165
	v_mul_f32_e32 v165, 0xbfb8aa3b, v78
	v_exp_f32_e32 v166, v165
	v_mul_f32_e32 v165, 0xbfb8aa3b, v79
	v_exp_f32_e32 v167, v165
	v_rcp_f32_e32 v165, v153
	v_add_f32_e32 v153, 1.0, v166
	v_rcp_f32_e32 v166, v153
	v_add_f32_e32 v153, 1.0, v167
	v_rcp_f32_e32 v167, v153
	v_pk_mul_f32 v[164:165], v[76:77], v[164:165]
	v_mul_f32_e32 v153, 0xbfb8aa3b, v72
	v_pk_mul_f32 v[164:165], v[100:101], v[164:165]
	v_exp_f32_e32 v153, v153
	v_cvt_pk_bf16_f32 v164, v164, v165
	v_mul_f32_e32 v165, 0xbfb8aa3b, v73
	v_exp_f32_e32 v168, v165
	v_pk_mul_f32 v[166:167], v[78:79], v[166:167]
	v_add_f32_e32 v153, 1.0, v153
	v_pk_mul_f32 v[166:167], v[102:103], v[166:167]
	v_lshlrev_b64 v[156:157], 11, v[156:157]
	v_cvt_pk_bf16_f32 v165, v166, v167
	v_mul_f32_e32 v167, 0xbfb8aa3b, v74
	v_rcp_f32_e32 v166, v153
	v_add_f32_e32 v153, 1.0, v168
	v_exp_f32_e32 v168, v167
	v_mul_f32_e32 v167, 0xbfb8aa3b, v75
	v_exp_f32_e32 v169, v167
	v_rcp_f32_e32 v167, v153
	v_add_f32_e32 v153, 1.0, v168
	v_rcp_f32_e32 v168, v153
	v_add_f32_e32 v153, 1.0, v169
	v_rcp_f32_e32 v169, v153
	v_lshl_add_u64 v[156:157], s[52:53], 0, v[156:157]
	v_lshl_add_u64 v[156:157], v[156:157], 0, v[136:137]
	v_pk_mul_f32 v[166:167], v[72:73], v[166:167]
	v_pk_mul_f32 v[168:169], v[74:75], v[168:169]
	v_pk_mul_f32 v[166:167], v[96:97], v[166:167]
	v_pk_mul_f32 v[168:169], v[98:99], v[168:169]
	v_add_co_u32_e32 v156, vcc, s76, v156
	v_cvt_pk_bf16_f32 v166, v166, v167
	v_cvt_pk_bf16_f32 v167, v168, v169
	v_addc_co_u32_e32 v157, vcc, 0, v157, vcc
	v_mul_f32_e32 v153, 0xbfb8aa3b, v68
	global_store_dwordx4 v[156:157], v[164:167], off offset:3072 nt
	v_or_b32_e32 v156, 48, v152
	v_exp_f32_e32 v153, v153
	v_mul_f32_e32 v164, 0xbfb8aa3b, v69
	v_ashrrev_i32_e32 v157, 31, v156
	v_exp_f32_e32 v165, v164
	v_lshlrev_b64 v[156:157], 11, v[156:157]
	v_lshl_add_u64 v[156:157], s[52:53], 0, v[156:157]
	v_lshl_add_u64 v[156:157], v[156:157], 0, v[136:137]
	v_add_f32_e32 v136, 1.0, v153
	v_mul_f32_e32 v153, 0xbfb8aa3b, v70
	v_rcp_f32_e32 v164, v136
	v_add_f32_e32 v136, 1.0, v165
	v_exp_f32_e32 v153, v153
	v_mul_f32_e32 v165, 0xbfb8aa3b, v71
	v_exp_f32_e32 v167, v165
	v_rcp_f32_e32 v165, v136
	v_add_f32_e32 v136, 1.0, v153
	v_rcp_f32_e32 v166, v136
	v_add_f32_e32 v136, 1.0, v167
	v_rcp_f32_e32 v167, v136
	v_mul_f32_e32 v136, 0xbfb8aa3b, v64
	v_exp_f32_e32 v136, v136
	v_mul_f32_e32 v153, 0xbfb8aa3b, v65
	v_exp_f32_e32 v153, v153
	v_pk_mul_f32 v[164:165], v[68:69], v[164:165]
	v_pk_mul_f32 v[166:167], v[70:71], v[166:167]
	v_pk_mul_f32 v[164:165], v[84:85], v[164:165]
	v_pk_mul_f32 v[166:167], v[86:87], v[166:167]
	v_add_f32_e32 v136, 1.0, v136
	v_cvt_pk_bf16_f32 v164, v164, v165
	v_cvt_pk_bf16_f32 v165, v166, v167
	v_rcp_f32_e32 v166, v136
	v_add_f32_e32 v136, 1.0, v153
	v_mul_f32_e32 v153, 0xbfb8aa3b, v66
	v_exp_f32_e32 v153, v153
	v_mul_f32_e32 v167, 0xbfb8aa3b, v67
	v_exp_f32_e32 v169, v167
	v_rcp_f32_e32 v167, v136
	v_add_f32_e32 v136, 1.0, v153
	v_rcp_f32_e32 v168, v136
	v_add_f32_e32 v136, 1.0, v169
	v_rcp_f32_e32 v169, v136
	v_mul_f32_e32 v136, 0xbfb8aa3b, v44
	v_exp_f32_e32 v136, v136
	v_mul_f32_e32 v153, 0xbfb8aa3b, v45
	v_exp_f32_e32 v153, v153
	v_pk_mul_f32 v[166:167], v[64:65], v[166:167]
	v_pk_mul_f32 v[168:169], v[66:67], v[168:169]
	v_pk_mul_f32 v[166:167], v[80:81], v[166:167]
	v_pk_mul_f32 v[168:169], v[82:83], v[168:169]
	v_add_co_u32_e32 v156, vcc, s76, v156
	v_cvt_pk_bf16_f32 v166, v166, v167
	v_cvt_pk_bf16_f32 v167, v168, v169
	v_addc_co_u32_e32 v157, vcc, 0, v157, vcc
	v_add_f32_e32 v136, 1.0, v136
	global_store_dwordx4 v[156:157], v[164:167], off offset:3072 nt
	v_rcp_f32_e32 v156, v136
	v_add_f32_e32 v136, 1.0, v153
	v_mul_f32_e32 v153, 0xbfb8aa3b, v46
	v_exp_f32_e32 v153, v153
	v_mul_f32_e32 v157, 0xbfb8aa3b, v47
	v_exp_f32_e32 v164, v157
	v_rcp_f32_e32 v157, v136
	v_add_f32_e32 v136, 1.0, v153
	v_rcp_f32_e32 v166, v136
	v_add_f32_e32 v136, 1.0, v164
	v_rcp_f32_e32 v167, v136
	v_mul_f32_e32 v136, 0xbfb8aa3b, v40
	v_exp_f32_e32 v136, v136
	v_mul_f32_e32 v153, 0xbfb8aa3b, v41
	v_pk_mul_f32 v[156:157], v[44:45], v[156:157]
	v_exp_f32_e32 v153, v153
	v_pk_mul_f32 v[156:157], v[60:61], v[156:157]
	v_add_f32_e32 v136, 1.0, v136
	v_cvt_pk_bf16_f32 v164, v156, v157
	v_pk_mul_f32 v[156:157], v[46:47], v[166:167]
	s_nop 0
	v_pk_mul_f32 v[156:157], v[62:63], v[156:157]
	s_nop 0
	v_cvt_pk_bf16_f32 v165, v156, v157
	v_rcp_f32_e32 v156, v136
	v_add_f32_e32 v136, 1.0, v153
	v_mul_f32_e32 v153, 0xbfb8aa3b, v42
	v_exp_f32_e32 v153, v153
	v_mul_f32_e32 v157, 0xbfb8aa3b, v43
	v_exp_f32_e32 v166, v157
	v_rcp_f32_e32 v157, v136
	v_add_f32_e32 v136, 1.0, v153
	v_rcp_f32_e32 v168, v136
	v_add_f32_e32 v136, 1.0, v166
	v_rcp_f32_e32 v169, v136
	v_pk_mul_f32 v[156:157], v[40:41], v[156:157]
	v_mul_f32_e32 v136, 0xbfb8aa3b, v28
	v_pk_mul_f32 v[156:157], v[56:57], v[156:157]
	v_exp_f32_e32 v136, v136
	v_mul_f32_e32 v153, 0xbfb8aa3b, v29
	v_cvt_pk_bf16_f32 v166, v156, v157
	v_pk_mul_f32 v[156:157], v[42:43], v[168:169]
	v_exp_f32_e32 v153, v153
	v_pk_mul_f32 v[156:157], v[58:59], v[156:157]
	v_add_f32_e32 v136, 1.0, v136
	v_cvt_pk_bf16_f32 v167, v156, v157
	v_add_co_u32_e32 v156, vcc, s77, v154
	s_nop 1
	v_addc_co_u32_e32 v157, vcc, 0, v155, vcc
	s_mov_b32 s100, 0
	v_add_co_u32_e32 v236, vcc, 0xc00, v156
	v_mov_b64_e32 v[232:233], v[164:165]
	v_mov_b64_e32 v[234:235], v[166:167]
	v_addc_co_u32_e32 v237, vcc, 0, v157, vcc
	v_rcp_f32_e32 v156, v136
	v_add_f32_e32 v136, 1.0, v153
	v_mul_f32_e32 v153, 0xbfb8aa3b, v30
	v_exp_f32_e32 v153, v153
	v_mul_f32_e32 v157, 0xbfb8aa3b, v31
	v_exp_f32_e32 v164, v157
	v_rcp_f32_e32 v157, v136
	v_add_f32_e32 v136, 1.0, v153
	v_rcp_f32_e32 v166, v136
	v_add_f32_e32 v136, 1.0, v164
	v_rcp_f32_e32 v167, v136
	v_mul_f32_e32 v136, 0xbfb8aa3b, v24
	v_exp_f32_e32 v136, v136
	v_mul_f32_e32 v153, 0xbfb8aa3b, v25
	v_pk_mul_f32 v[156:157], v[28:29], v[156:157]
	v_exp_f32_e32 v153, v153
	v_pk_mul_f32 v[156:157], v[52:53], v[156:157]
	v_add_f32_e32 v136, 1.0, v136
	v_cvt_pk_bf16_f32 v164, v156, v157
	v_pk_mul_f32 v[156:157], v[30:31], v[166:167]
	s_nop 0
	v_pk_mul_f32 v[156:157], v[54:55], v[156:157]
	s_nop 0
	v_cvt_pk_bf16_f32 v165, v156, v157
	v_rcp_f32_e32 v156, v136
	v_add_f32_e32 v136, 1.0, v153
	v_mul_f32_e32 v153, 0xbfb8aa3b, v26
	v_exp_f32_e32 v153, v153
	v_mul_f32_e32 v157, 0xbfb8aa3b, v27
	v_exp_f32_e32 v166, v157
	v_rcp_f32_e32 v157, v136
	v_add_f32_e32 v136, 1.0, v153
	v_rcp_f32_e32 v168, v136
	v_add_f32_e32 v136, 1.0, v166
	v_rcp_f32_e32 v169, v136
	v_pk_mul_f32 v[156:157], v[24:25], v[156:157]
	v_mul_f32_e32 v136, 0xbfb8aa3b, v12
	v_pk_mul_f32 v[156:157], v[48:49], v[156:157]
	v_exp_f32_e32 v136, v136
	v_mul_f32_e32 v153, 0xbfb8aa3b, v13
	v_cvt_pk_bf16_f32 v166, v156, v157
	v_pk_mul_f32 v[156:157], v[26:27], v[168:169]
	v_exp_f32_e32 v153, v153
	v_pk_mul_f32 v[156:157], v[50:51], v[156:157]
	v_add_f32_e32 v136, 1.0, v136
	v_cvt_pk_bf16_f32 v167, v156, v157
	v_add_co_u32_e32 v156, vcc, s78, v154
	s_nop 1
	v_addc_co_u32_e32 v157, vcc, 0, v155, vcc
	v_add_co_u32_e32 v242, vcc, 0xc00, v156
	v_mov_b64_e32 v[238:239], v[164:165]
	v_mov_b64_e32 v[240:241], v[166:167]
	v_addc_co_u32_e32 v243, vcc, 0, v157, vcc
	v_rcp_f32_e32 v156, v136
	v_add_f32_e32 v136, 1.0, v153
	v_mul_f32_e32 v153, 0xbfb8aa3b, v14
	v_exp_f32_e32 v153, v153
	v_mul_f32_e32 v157, 0xbfb8aa3b, v15
	v_exp_f32_e32 v164, v157
	v_rcp_f32_e32 v157, v136
	v_add_f32_e32 v136, 1.0, v153
	v_rcp_f32_e32 v166, v136
	v_add_f32_e32 v136, 1.0, v164
	v_rcp_f32_e32 v167, v136
	v_mul_f32_e32 v136, 0xbfb8aa3b, v8
	v_exp_f32_e32 v136, v136
	v_mul_f32_e32 v153, 0xbfb8aa3b, v9
	v_pk_mul_f32 v[156:157], v[12:13], v[156:157]
	v_exp_f32_e32 v153, v153
	v_pk_mul_f32 v[156:157], v[36:37], v[156:157]
	v_add_f32_e32 v136, 1.0, v136
	v_cvt_pk_bf16_f32 v164, v156, v157
	v_pk_mul_f32 v[156:157], v[14:15], v[166:167]
	s_nop 0
	v_pk_mul_f32 v[156:157], v[38:39], v[156:157]
	s_nop 0
	v_cvt_pk_bf16_f32 v165, v156, v157
	v_rcp_f32_e32 v156, v136
	v_add_f32_e32 v136, 1.0, v153
	v_mul_f32_e32 v153, 0xbfb8aa3b, v10
	v_exp_f32_e32 v153, v153
	v_mul_f32_e32 v157, 0xbfb8aa3b, v11
	v_exp_f32_e32 v166, v157
	v_rcp_f32_e32 v157, v136
	v_add_f32_e32 v136, 1.0, v153
	v_rcp_f32_e32 v168, v136
	v_add_f32_e32 v136, 1.0, v166
	v_rcp_f32_e32 v169, v136
	v_pk_mul_f32 v[156:157], v[8:9], v[156:157]
	v_mul_f32_e32 v136, 0xbfb8aa3b, v4
	v_pk_mul_f32 v[156:157], v[32:33], v[156:157]
	v_exp_f32_e32 v136, v136
	v_mul_f32_e32 v153, 0xbfb8aa3b, v5
	v_cvt_pk_bf16_f32 v166, v156, v157
	v_pk_mul_f32 v[156:157], v[10:11], v[168:169]
	v_exp_f32_e32 v153, v153
	v_pk_mul_f32 v[156:157], v[34:35], v[156:157]
	v_add_f32_e32 v136, 1.0, v136
	v_cvt_pk_bf16_f32 v167, v156, v157
	v_add_co_u32_e32 v156, vcc, s79, v154
	s_nop 1
	v_addc_co_u32_e32 v157, vcc, 0, v155, vcc
	v_add_co_u32_e32 v248, vcc, 0xc00, v156
	v_mov_b64_e32 v[244:245], v[164:165]
	v_mov_b64_e32 v[246:247], v[166:167]
	v_addc_co_u32_e32 v249, vcc, 0, v157, vcc
	v_rcp_f32_e32 v156, v136
	v_add_f32_e32 v136, 1.0, v153
	v_mul_f32_e32 v153, 0xbfb8aa3b, v6
	v_exp_f32_e32 v153, v153
	v_mul_f32_e32 v157, 0xbfb8aa3b, v7
	v_exp_f32_e32 v164, v157
	v_rcp_f32_e32 v157, v136
	v_add_f32_e32 v136, 1.0, v153
	v_rcp_f32_e32 v166, v136
	v_add_f32_e32 v136, 1.0, v164
	v_rcp_f32_e32 v167, v136
	v_mul_f32_e32 v136, 0xbfb8aa3b, v0
	v_exp_f32_e32 v136, v136
	v_mul_f32_e32 v153, 0xbfb8aa3b, v1
	v_pk_mul_f32 v[156:157], v[4:5], v[156:157]
	v_exp_f32_e32 v153, v153
	v_pk_mul_f32 v[156:157], v[20:21], v[156:157]
	v_add_f32_e32 v136, 1.0, v136
	v_cvt_pk_bf16_f32 v164, v156, v157
	v_pk_mul_f32 v[156:157], v[6:7], v[166:167]
	v_add_co_u32_e32 v154, vcc, 0x1a056000, v154
	v_pk_mul_f32 v[156:157], v[22:23], v[156:157]
	s_nop 0
	v_addc_co_u32_e32 v155, vcc, 0, v155, vcc
	v_cvt_pk_bf16_f32 v165, v156, v157
	v_rcp_f32_e32 v156, v136
	v_add_f32_e32 v136, 1.0, v153
	v_mul_f32_e32 v153, 0xbfb8aa3b, v2
	v_exp_f32_e32 v153, v153
	v_mul_f32_e32 v157, 0xbfb8aa3b, v3
	v_exp_f32_e32 v166, v157
	v_rcp_f32_e32 v157, v136
	v_add_f32_e32 v136, 1.0, v153
	v_rcp_f32_e32 v168, v136
	v_add_f32_e32 v136, 1.0, v166
	v_rcp_f32_e32 v169, v136
	v_pk_mul_f32 v[156:157], v[0:1], v[156:157]
	s_nop 0
	v_pk_mul_f32 v[156:157], v[16:17], v[156:157]
	s_nop 0
	v_cvt_pk_bf16_f32 v166, v156, v157
	v_pk_mul_f32 v[156:157], v[2:3], v[168:169]
	s_nop 0
	v_pk_mul_f32 v[156:157], v[18:19], v[156:157]
	s_nop 0
	v_cvt_pk_bf16_f32 v167, v156, v157
	v_add_co_u32_e32 v254, vcc, 0xc00, v154
	v_mov_b64_e32 v[250:251], v[164:165]
	v_mov_b64_e32 v[252:253], v[166:167]
	v_addc_co_u32_e32 v255, vcc, 0, v155, vcc

.LBB0_204:
	s_andn2_b64 vcc, exec, s[52:53]
	s_cbranch_vccnz .LBB0_206
	s_lshl_b32 s47, s94, 8
	s_add_u32 s52, s10, s47
	v_ashrrev_i32_e32 v153, 31, v152
	s_addc_u32 s53, s11, 0
	v_lshlrev_b64 v[154:155], 11, v[152:153]
	v_lshl_add_u64 v[164:165], s[52:53], 0, v[154:155]
	v_lshlrev_b32_e32 v136, 1, v138
	v_pk_mul_f32 v[156:157], v[126:127], v[110:111]
	v_pk_mul_f32 v[154:155], v[124:125], v[108:109]
	v_pk_mul_f32 v[166:167], v[122:123], v[106:107]
	v_lshl_add_u64 v[164:165], v[164:165], 0, v[136:137]
	v_pk_mul_f32 v[168:169], v[120:121], v[104:105]
	v_cvt_pk_bf16_f32 v154, v154, v155
	v_cvt_pk_bf16_f32 v155, v156, v157
	v_cvt_pk_bf16_f32 v157, v166, v167
	v_add_co_u32_e32 v166, vcc, s80, v164
	v_cvt_pk_bf16_f32 v156, v168, v169
	s_nop 0
	v_addc_co_u32_e32 v167, vcc, 0, v165, vcc
	global_store_dwordx4 v[166:167], v[154:157], off offset:1024 nt
	v_pk_mul_f32 v[168:169], v[114:115], v[90:91]
	v_pk_mul_f32 v[170:171], v[112:113], v[88:89]
	v_or_b32_e32 v154, 16, v152
	v_ashrrev_i32_e32 v155, 31, v154
	v_lshlrev_b64 v[154:155], 11, v[154:155]
	v_lshl_add_u64 v[154:155], s[52:53], 0, v[154:155]
	v_lshl_add_u64 v[166:167], v[154:155], 0, v[136:137]
	v_pk_mul_f32 v[156:157], v[118:119], v[94:95]
	v_pk_mul_f32 v[154:155], v[116:117], v[92:93]
	v_add_co_u32_e32 v166, vcc, s80, v166
	v_cvt_pk_bf16_f32 v154, v154, v155
	v_cvt_pk_bf16_f32 v155, v156, v157
	v_cvt_pk_bf16_f32 v156, v170, v171
	v_cvt_pk_bf16_f32 v157, v168, v169
	v_addc_co_u32_e32 v167, vcc, 0, v167, vcc
	global_store_dwordx4 v[166:167], v[154:157], off offset:1024 nt
	v_pk_mul_f32 v[168:169], v[98:99], v[74:75]
	v_pk_mul_f32 v[170:171], v[96:97], v[72:73]
	v_or_b32_e32 v154, 32, v152
	v_ashrrev_i32_e32 v155, 31, v154
	v_lshlrev_b64 v[154:155], 11, v[154:155]
	v_lshl_add_u64 v[154:155], s[52:53], 0, v[154:155]
	v_lshl_add_u64 v[166:167], v[154:155], 0, v[136:137]
	v_pk_mul_f32 v[156:157], v[102:103], v[78:79]
	v_pk_mul_f32 v[154:155], v[100:101], v[76:77]
	v_add_co_u32_e32 v166, vcc, s80, v166
	v_cvt_pk_bf16_f32 v154, v154, v155
	v_cvt_pk_bf16_f32 v155, v156, v157
	v_cvt_pk_bf16_f32 v156, v170, v171
	v_cvt_pk_bf16_f32 v157, v168, v169
	v_addc_co_u32_e32 v167, vcc, 0, v167, vcc
	global_store_dwordx4 v[166:167], v[154:157], off offset:1024 nt
	v_pk_mul_f32 v[168:169], v[82:83], v[66:67]
	v_pk_mul_f32 v[170:171], v[80:81], v[64:65]
	v_or_b32_e32 v154, 48, v152
	v_ashrrev_i32_e32 v155, 31, v154
	v_lshlrev_b64 v[154:155], 11, v[154:155]
	v_lshl_add_u64 v[154:155], s[52:53], 0, v[154:155]
	v_lshl_add_u64 v[166:167], v[154:155], 0, v[136:137]
	v_pk_mul_f32 v[156:157], v[86:87], v[70:71]
	v_pk_mul_f32 v[154:155], v[84:85], v[68:69]
	v_add_co_u32_e32 v166, vcc, s80, v166
	v_cvt_pk_bf16_f32 v154, v154, v155
	v_cvt_pk_bf16_f32 v155, v156, v157
	v_cvt_pk_bf16_f32 v156, v170, v171
	v_cvt_pk_bf16_f32 v157, v168, v169
	v_addc_co_u32_e32 v167, vcc, 0, v167, vcc
	global_store_dwordx4 v[166:167], v[154:157], off offset:1024 nt
	v_pk_mul_f32 v[166:167], v[58:59], v[42:43]
	v_pk_mul_f32 v[168:169], v[56:57], v[40:41]
	v_pk_mul_f32 v[156:157], v[62:63], v[46:47]
	v_pk_mul_f32 v[154:155], v[60:61], v[44:45]
	s_nop 0
	v_cvt_pk_bf16_f32 v154, v154, v155
	v_cvt_pk_bf16_f32 v155, v156, v157
	v_cvt_pk_bf16_f32 v157, v166, v167
	v_add_co_u32_e32 v166, vcc, s81, v164
	v_cvt_pk_bf16_f32 v156, v168, v169
	s_nop 0
	v_addc_co_u32_e32 v167, vcc, 0, v165, vcc
	s_mov_b32 s100, 0
	v_add_co_u32_e32 v236, vcc, 0x400, v166
	v_mov_b64_e32 v[232:233], v[154:155]
	v_mov_b64_e32 v[234:235], v[156:157]
	v_addc_co_u32_e32 v237, vcc, 0, v167, vcc
	v_pk_mul_f32 v[166:167], v[50:51], v[26:27]
	v_pk_mul_f32 v[168:169], v[48:49], v[24:25]
	v_pk_mul_f32 v[156:157], v[54:55], v[30:31]
	v_pk_mul_f32 v[154:155], v[52:53], v[28:29]
	s_nop 0
	v_cvt_pk_bf16_f32 v154, v154, v155
	v_cvt_pk_bf16_f32 v155, v156, v157
	v_cvt_pk_bf16_f32 v157, v166, v167
	v_add_co_u32_e32 v166, vcc, s82, v164
	v_cvt_pk_bf16_f32 v156, v168, v169
	s_nop 0
	v_addc_co_u32_e32 v167, vcc, 0, v165, vcc
	v_add_co_u32_e32 v242, vcc, 0x400, v166
	v_mov_b64_e32 v[238:239], v[154:155]
	v_mov_b64_e32 v[240:241], v[156:157]
	v_addc_co_u32_e32 v243, vcc, 0, v167, vcc
	v_pk_mul_f32 v[166:167], v[34:35], v[10:11]
	v_pk_mul_f32 v[168:169], v[32:33], v[8:9]
	v_pk_mul_f32 v[156:157], v[38:39], v[14:15]
	v_pk_mul_f32 v[154:155], v[36:37], v[12:13]
	s_nop 0
	v_cvt_pk_bf16_f32 v154, v154, v155
	v_cvt_pk_bf16_f32 v155, v156, v157
	v_cvt_pk_bf16_f32 v157, v166, v167
	v_add_co_u32_e32 v166, vcc, s83, v164
	v_cvt_pk_bf16_f32 v156, v168, v169
	s_nop 0
	v_addc_co_u32_e32 v167, vcc, 0, v165, vcc
	v_add_co_u32_e32 v248, vcc, 0x400, v166
	v_mov_b64_e32 v[244:245], v[154:155]
	v_mov_b64_e32 v[246:247], v[156:157]
	v_addc_co_u32_e32 v249, vcc, 0, v167, vcc
	v_pk_mul_f32 v[166:167], v[18:19], v[2:3]
	v_pk_mul_f32 v[168:169], v[16:17], v[0:1]
	v_pk_mul_f32 v[156:157], v[22:23], v[6:7]
	v_pk_mul_f32 v[154:155], v[20:21], v[4:5]
	v_add_co_u32_e32 v164, vcc, 0x16057000, v164
	v_cvt_pk_bf16_f32 v154, v154, v155
	v_cvt_pk_bf16_f32 v155, v156, v157
	v_cvt_pk_bf16_f32 v156, v168, v169
	v_cvt_pk_bf16_f32 v157, v166, v167
	v_addc_co_u32_e32 v165, vcc, 0, v165, vcc
	v_add_co_u32_e32 v254, vcc, 0x400, v164
	v_mov_b64_e32 v[250:251], v[154:155]
	v_mov_b64_e32 v[252:253], v[156:157]
	v_addc_co_u32_e32 v255, vcc, 0, v165, vcc

.LBB0_207:
	s_andn2_b64 vcc, exec, s[52:53]
	s_cbranch_vccnz .LBB0_209
	s_lshl_b32 s47, s94, 9
	s_add_u32 s52, s10, s47
	v_ashrrev_i32_e32 v153, 31, v152
	s_addc_u32 s53, s11, 0
	v_lshlrev_b64 v[154:155], 11, v[152:153]
	v_lshl_add_u64 v[154:155], s[52:53], 0, v[154:155]
	v_lshlrev_b32_e32 v136, 1, v138
	v_lshl_add_u64 v[164:165], v[154:155], 0, v[136:137]
	v_add_co_u32_e32 v168, vcc, s84, v164
	v_cvt_pk_bf16_f32 v154, v124, v125
	v_cvt_pk_bf16_f32 v155, v126, v127
	v_cvt_pk_bf16_f32 v156, v120, v121
	v_cvt_pk_bf16_f32 v157, v122, v123
	v_addc_co_u32_e32 v169, vcc, 0, v165, vcc
	v_lshl_add_u64 v[166:167], v[164:165], 0, s[22:23]
	global_store_dwordx4 v[168:169], v[154:157], off nt
	s_nop 1
	v_cvt_pk_bf16_f32 v154, v108, v109
	v_cvt_pk_bf16_f32 v155, v110, v111
	v_cvt_pk_bf16_f32 v156, v104, v105
	v_cvt_pk_bf16_f32 v157, v106, v107
	global_store_dwordx4 v[166:167], v[154:157], off offset:256 nt
	s_nop 1
	v_or_b32_e32 v154, 16, v152
	v_ashrrev_i32_e32 v155, 31, v154
	v_lshlrev_b64 v[154:155], 11, v[154:155]
	v_lshl_add_u64 v[154:155], s[52:53], 0, v[154:155]
	v_lshl_add_u64 v[166:167], v[154:155], 0, v[136:137]
	v_lshl_add_u64 v[168:169], v[166:167], 0, s[22:23]
	v_add_co_u32_e32 v166, vcc, s84, v166
	v_cvt_pk_bf16_f32 v154, v116, v117
	v_cvt_pk_bf16_f32 v155, v118, v119
	v_cvt_pk_bf16_f32 v156, v112, v113
	v_cvt_pk_bf16_f32 v157, v114, v115
	v_addc_co_u32_e32 v167, vcc, 0, v167, vcc
	global_store_dwordx4 v[166:167], v[154:157], off nt
	s_nop 1
	v_cvt_pk_bf16_f32 v154, v92, v93
	v_cvt_pk_bf16_f32 v155, v94, v95
	v_cvt_pk_bf16_f32 v156, v88, v89
	v_cvt_pk_bf16_f32 v157, v90, v91
	global_store_dwordx4 v[168:169], v[154:157], off offset:256 nt
	s_nop 1
	v_or_b32_e32 v154, 32, v152
	v_ashrrev_i32_e32 v155, 31, v154
	v_lshlrev_b64 v[154:155], 11, v[154:155]
	v_lshl_add_u64 v[154:155], s[52:53], 0, v[154:155]
	v_lshl_add_u64 v[166:167], v[154:155], 0, v[136:137]
	v_lshl_add_u64 v[168:169], v[166:167], 0, s[22:23]
	v_add_co_u32_e32 v166, vcc, s84, v166
	v_cvt_pk_bf16_f32 v154, v100, v101
	v_cvt_pk_bf16_f32 v155, v102, v103
	v_cvt_pk_bf16_f32 v156, v96, v97
	v_cvt_pk_bf16_f32 v157, v98, v99
	v_addc_co_u32_e32 v167, vcc, 0, v167, vcc
	global_store_dwordx4 v[166:167], v[154:157], off nt
	s_nop 1
	v_cvt_pk_bf16_f32 v154, v76, v77
	v_cvt_pk_bf16_f32 v155, v78, v79
	v_cvt_pk_bf16_f32 v156, v72, v73
	v_cvt_pk_bf16_f32 v157, v74, v75
	global_store_dwordx4 v[168:169], v[154:157], off offset:256 nt
	s_nop 1
	v_or_b32_e32 v154, 48, v152
	v_ashrrev_i32_e32 v155, 31, v154
	v_lshlrev_b64 v[154:155], 11, v[154:155]
	v_lshl_add_u64 v[154:155], s[52:53], 0, v[154:155]
	v_lshl_add_u64 v[166:167], v[154:155], 0, v[136:137]
	v_lshl_add_u64 v[168:169], v[166:167], 0, s[22:23]
	v_add_co_u32_e32 v166, vcc, s84, v166
	v_cvt_pk_bf16_f32 v154, v84, v85
	v_cvt_pk_bf16_f32 v155, v86, v87
	v_cvt_pk_bf16_f32 v156, v80, v81
	v_cvt_pk_bf16_f32 v157, v82, v83
	v_addc_co_u32_e32 v167, vcc, 0, v167, vcc
	global_store_dwordx4 v[166:167], v[154:157], off nt
	v_lshl_add_u64 v[166:167], v[164:165], 0, s[24:25]
	s_nop 0
	v_cvt_pk_bf16_f32 v154, v68, v69
	v_cvt_pk_bf16_f32 v155, v70, v71
	v_cvt_pk_bf16_f32 v156, v64, v65
	v_cvt_pk_bf16_f32 v157, v66, v67
	global_store_dwordx4 v[168:169], v[154:157], off offset:256 nt
	v_add_co_u32_e32 v168, vcc, s85, v164
	s_nop 0
	v_cvt_pk_bf16_f32 v154, v60, v61
	v_cvt_pk_bf16_f32 v155, v62, v63
	v_cvt_pk_bf16_f32 v156, v56, v57
	v_cvt_pk_bf16_f32 v157, v58, v59
	v_addc_co_u32_e32 v169, vcc, 0, v165, vcc
	s_mov_b32 s100, 0
	v_mov_b64_e32 v[236:237], v[168:169]
	v_mov_b64_e32 v[232:233], v[154:155]
	v_mov_b64_e32 v[234:235], v[156:157]
	v_add_co_u32_e32 v168, vcc, s86, v164
	s_nop 0
	v_cvt_pk_bf16_f32 v154, v44, v45
	v_cvt_pk_bf16_f32 v155, v46, v47
	v_cvt_pk_bf16_f32 v156, v40, v41
	v_cvt_pk_bf16_f32 v157, v42, v43
	global_store_dwordx4 v[166:167], v[154:157], off offset:256 nt
	v_addc_co_u32_e32 v169, vcc, 0, v165, vcc
	s_nop 0
	v_cvt_pk_bf16_f32 v154, v52, v53
	v_cvt_pk_bf16_f32 v155, v54, v55
	v_cvt_pk_bf16_f32 v156, v48, v49
	v_cvt_pk_bf16_f32 v157, v50, v51
	v_lshl_add_u64 v[166:167], v[164:165], 0, s[26:27]
	v_mov_b64_e32 v[242:243], v[168:169]
	v_mov_b64_e32 v[238:239], v[154:155]
	v_mov_b64_e32 v[240:241], v[156:157]
	v_add_co_u32_e32 v168, vcc, s87, v164
	s_nop 0
	v_cvt_pk_bf16_f32 v154, v28, v29
	v_cvt_pk_bf16_f32 v155, v30, v31
	v_cvt_pk_bf16_f32 v156, v24, v25
	v_cvt_pk_bf16_f32 v157, v26, v27
	global_store_dwordx4 v[166:167], v[154:157], off offset:256 nt
	v_addc_co_u32_e32 v169, vcc, 0, v165, vcc
	s_nop 0
	v_cvt_pk_bf16_f32 v154, v36, v37
	v_cvt_pk_bf16_f32 v155, v38, v39
	v_cvt_pk_bf16_f32 v156, v32, v33
	v_cvt_pk_bf16_f32 v157, v34, v35
	v_lshl_add_u64 v[166:167], v[164:165], 0, s[28:29]
	v_mov_b64_e32 v[248:249], v[168:169]
	v_mov_b64_e32 v[244:245], v[154:155]
	v_mov_b64_e32 v[246:247], v[156:157]
	s_nop 1
	v_cvt_pk_bf16_f32 v154, v12, v13
	v_cvt_pk_bf16_f32 v155, v14, v15
	v_cvt_pk_bf16_f32 v156, v8, v9
	v_cvt_pk_bf16_f32 v157, v10, v11
	global_store_dwordx4 v[166:167], v[154:157], off offset:256 nt
	v_lshl_add_u64 v[166:167], v[164:165], 0, s[30:31]
	v_add_co_u32_e32 v164, vcc, s88, v164
	v_cvt_pk_bf16_f32 v154, v20, v21
	v_cvt_pk_bf16_f32 v155, v22, v23
	v_cvt_pk_bf16_f32 v156, v16, v17
	v_cvt_pk_bf16_f32 v157, v18, v19
	v_addc_co_u32_e32 v165, vcc, 0, v165, vcc
	v_mov_b64_e32 v[254:255], v[164:165]
	v_mov_b64_e32 v[250:251], v[154:155]
	v_mov_b64_e32 v[252:253], v[156:157]
	s_nop 1
	v_cvt_pk_bf16_f32 v154, v4, v5
	v_cvt_pk_bf16_f32 v155, v6, v7
	v_cvt_pk_bf16_f32 v156, v0, v1
	v_cvt_pk_bf16_f32 v157, v2, v3
	global_store_dwordx4 v[166:167], v[154:157], off offset:256 nt

.LBB0_210:
	s_andn2_b64 vcc, exec, s[52:53]
	s_cbranch_vccnz .LBB0_212
	s_lshl_b32 s47, s94, 8
	s_add_i32 s54, s47, 0xfffffe00
	s_cmp_lt_i32 s94, 2
	s_cselect_b64 vcc, -1, 0
	s_and_b64 s[52:53], vcc, exec
	s_cselect_b32 s52, s47, s54
	s_cselect_b32 s47, s89, 0x14000000
	s_add_u32 s47, s10, s47
	s_addc_u32 s54, s11, 0
	s_ashr_i32 s53, s52, 31
	s_lshl_b64 s[52:53], s[52:53], 1
	s_add_u32 s52, s47, s52
	v_cndmask_b32_e32 v154, 1.0, v163, vcc
	s_addc_u32 s53, s54, s53
	v_lshlrev_b32_e32 v136, 1, v138
	v_ashrrev_i32_e32 v153, 31, v152
	v_lshl_add_u64 v[168:169], s[52:53], 0, v[136:137]
	v_lshlrev_b64 v[156:157], 10, v[152:153]
	v_pk_mul_f32 v[166:167], v[154:155], v[126:127] op_sel_hi:[0,1]
	v_pk_mul_f32 v[164:165], v[154:155], v[124:125] op_sel_hi:[0,1]
	v_pk_mul_f32 v[170:171], v[154:155], v[122:123] op_sel_hi:[0,1]
	v_pk_mul_f32 v[172:173], v[154:155], v[120:121] op_sel_hi:[0,1]
	v_lshl_add_u64 v[156:157], v[168:169], 0, v[156:157]
	v_cvt_pk_bf16_f32 v164, v164, v165
	v_cvt_pk_bf16_f32 v165, v166, v167
	v_cvt_pk_bf16_f32 v166, v172, v173
	v_cvt_pk_bf16_f32 v167, v170, v171
	global_store_dwordx4 v[156:157], v[164:167], off nt
	v_pk_mul_f32 v[170:171], v[154:155], v[106:107] op_sel_hi:[0,1]
	v_pk_mul_f32 v[172:173], v[154:155], v[104:105] op_sel_hi:[0,1]
	v_pk_mul_f32 v[166:167], v[154:155], v[110:111] op_sel_hi:[0,1]
	v_pk_mul_f32 v[164:165], v[154:155], v[108:109] op_sel_hi:[0,1]
	v_cvt_pk_bf16_f32 v164, v164, v165
	v_cvt_pk_bf16_f32 v165, v166, v167
	v_cvt_pk_bf16_f32 v166, v172, v173
	v_cvt_pk_bf16_f32 v167, v170, v171
	global_store_dwordx4 v[156:157], v[164:167], off offset:256 nt
	v_pk_mul_f32 v[172:173], v[154:155], v[114:115] op_sel_hi:[0,1]
	v_pk_mul_f32 v[174:175], v[154:155], v[112:113] op_sel_hi:[0,1]
	v_or_b32_e32 v164, 16, v152
	v_ashrrev_i32_e32 v165, 31, v164
	v_lshlrev_b64 v[164:165], 10, v[164:165]
	v_lshl_add_u64 v[170:171], v[168:169], 0, v[164:165]
	v_pk_mul_f32 v[166:167], v[154:155], v[118:119] op_sel_hi:[0,1]
	v_pk_mul_f32 v[164:165], v[154:155], v[116:117] op_sel_hi:[0,1]
	v_cvt_pk_bf16_f32 v164, v164, v165
	v_cvt_pk_bf16_f32 v165, v166, v167
	v_cvt_pk_bf16_f32 v166, v174, v175
	v_cvt_pk_bf16_f32 v167, v172, v173
	global_store_dwordx4 v[170:171], v[164:167], off nt
	v_pk_mul_f32 v[172:173], v[154:155], v[90:91] op_sel_hi:[0,1]
	v_pk_mul_f32 v[174:175], v[154:155], v[88:89] op_sel_hi:[0,1]
	v_pk_mul_f32 v[166:167], v[154:155], v[94:95] op_sel_hi:[0,1]
	v_pk_mul_f32 v[164:165], v[154:155], v[92:93] op_sel_hi:[0,1]
	v_cvt_pk_bf16_f32 v164, v164, v165
	v_cvt_pk_bf16_f32 v165, v166, v167
	v_cvt_pk_bf16_f32 v166, v174, v175
	v_cvt_pk_bf16_f32 v167, v172, v173
	global_store_dwordx4 v[170:171], v[164:167], off offset:256 nt
	v_pk_mul_f32 v[172:173], v[154:155], v[98:99] op_sel_hi:[0,1]
	v_pk_mul_f32 v[174:175], v[154:155], v[96:97] op_sel_hi:[0,1]
	v_or_b32_e32 v164, 32, v152
	v_ashrrev_i32_e32 v165, 31, v164
	v_lshlrev_b64 v[164:165], 10, v[164:165]
	v_lshl_add_u64 v[170:171], v[168:169], 0, v[164:165]
	v_pk_mul_f32 v[166:167], v[154:155], v[102:103] op_sel_hi:[0,1]
	v_pk_mul_f32 v[164:165], v[154:155], v[100:101] op_sel_hi:[0,1]
	v_cvt_pk_bf16_f32 v164, v164, v165
	v_cvt_pk_bf16_f32 v165, v166, v167
	v_cvt_pk_bf16_f32 v166, v174, v175
	v_cvt_pk_bf16_f32 v167, v172, v173
	global_store_dwordx4 v[170:171], v[164:167], off nt
	v_pk_mul_f32 v[172:173], v[154:155], v[74:75] op_sel_hi:[0,1]
	v_pk_mul_f32 v[174:175], v[154:155], v[72:73] op_sel_hi:[0,1]
	v_pk_mul_f32 v[166:167], v[154:155], v[78:79] op_sel_hi:[0,1]
	v_pk_mul_f32 v[164:165], v[154:155], v[76:77] op_sel_hi:[0,1]
	v_cvt_pk_bf16_f32 v164, v164, v165
	v_cvt_pk_bf16_f32 v165, v166, v167
	v_cvt_pk_bf16_f32 v166, v174, v175
	v_cvt_pk_bf16_f32 v167, v172, v173
	global_store_dwordx4 v[170:171], v[164:167], off offset:256 nt
	v_pk_mul_f32 v[170:171], v[154:155], v[82:83] op_sel_hi:[0,1]
	v_pk_mul_f32 v[172:173], v[154:155], v[80:81] op_sel_hi:[0,1]
	v_or_b32_e32 v164, 48, v152
	v_ashrrev_i32_e32 v165, 31, v164
	v_lshlrev_b64 v[164:165], 10, v[164:165]
	v_lshl_add_u64 v[168:169], v[168:169], 0, v[164:165]
	v_pk_mul_f32 v[166:167], v[154:155], v[86:87] op_sel_hi:[0,1]
	v_pk_mul_f32 v[164:165], v[154:155], v[84:85] op_sel_hi:[0,1]
	v_cvt_pk_bf16_f32 v164, v164, v165
	v_cvt_pk_bf16_f32 v165, v166, v167
	v_cvt_pk_bf16_f32 v166, v172, v173
	v_cvt_pk_bf16_f32 v167, v170, v171
	global_store_dwordx4 v[168:169], v[164:167], off nt
	v_pk_mul_f32 v[170:171], v[154:155], v[66:67] op_sel_hi:[0,1]
	v_pk_mul_f32 v[172:173], v[154:155], v[64:65] op_sel_hi:[0,1]
	v_pk_mul_f32 v[166:167], v[154:155], v[70:71] op_sel_hi:[0,1]
	v_pk_mul_f32 v[164:165], v[154:155], v[68:69] op_sel_hi:[0,1]
	v_cvt_pk_bf16_f32 v164, v164, v165
	v_cvt_pk_bf16_f32 v165, v166, v167
	v_cvt_pk_bf16_f32 v166, v172, v173
	v_cvt_pk_bf16_f32 v167, v170, v171
	global_store_dwordx4 v[168:169], v[164:167], off offset:256 nt
	v_pk_mul_f32 v[170:171], v[154:155], v[58:59] op_sel_hi:[0,1]
	v_pk_mul_f32 v[172:173], v[154:155], v[56:57] op_sel_hi:[0,1]
	v_pk_mul_f32 v[166:167], v[154:155], v[62:63] op_sel_hi:[0,1]
	v_pk_mul_f32 v[164:165], v[154:155], v[60:61] op_sel_hi:[0,1]
	v_cvt_pk_bf16_f32 v164, v164, v165
	v_cvt_pk_bf16_f32 v165, v166, v167
	v_cvt_pk_bf16_f32 v167, v170, v171
	v_add_co_u32_e32 v170, vcc, s90, v156
	v_cvt_pk_bf16_f32 v166, v172, v173
	s_nop 0
	v_addc_co_u32_e32 v171, vcc, 0, v157, vcc
	s_mov_b32 s100, 0
	v_mov_b64_e32 v[236:237], v[170:171]
	v_mov_b64_e32 v[232:233], v[164:165]
	v_mov_b64_e32 v[234:235], v[166:167]
	v_pk_mul_f32 v[170:171], v[154:155], v[42:43] op_sel_hi:[0,1]
	v_pk_mul_f32 v[172:173], v[154:155], v[40:41] op_sel_hi:[0,1]
	v_pk_mul_f32 v[166:167], v[154:155], v[46:47] op_sel_hi:[0,1]
	v_pk_mul_f32 v[164:165], v[154:155], v[44:45] op_sel_hi:[0,1]
	v_lshl_add_u64 v[168:169], v[156:157], 0, s[34:35]
	v_cvt_pk_bf16_f32 v164, v164, v165
	v_cvt_pk_bf16_f32 v165, v166, v167
	v_cvt_pk_bf16_f32 v166, v172, v173
	v_cvt_pk_bf16_f32 v167, v170, v171
	global_store_dwordx4 v[168:169], v[164:167], off offset:256 nt
	v_pk_mul_f32 v[170:171], v[154:155], v[50:51] op_sel_hi:[0,1]
	v_pk_mul_f32 v[172:173], v[154:155], v[48:49] op_sel_hi:[0,1]
	v_pk_mul_f32 v[166:167], v[154:155], v[54:55] op_sel_hi:[0,1]
	v_pk_mul_f32 v[164:165], v[154:155], v[52:53] op_sel_hi:[0,1]
	v_cvt_pk_bf16_f32 v164, v164, v165
	v_cvt_pk_bf16_f32 v165, v166, v167
	v_cvt_pk_bf16_f32 v167, v170, v171
	v_add_co_u32_e32 v170, vcc, s91, v156
	v_cvt_pk_bf16_f32 v166, v172, v173
	s_nop 0
	v_addc_co_u32_e32 v171, vcc, 0, v157, vcc
	v_mov_b64_e32 v[242:243], v[170:171]
	v_mov_b64_e32 v[238:239], v[164:165]
	v_mov_b64_e32 v[240:241], v[166:167]
	v_pk_mul_f32 v[170:171], v[154:155], v[26:27] op_sel_hi:[0,1]
	v_pk_mul_f32 v[172:173], v[154:155], v[24:25] op_sel_hi:[0,1]
	v_pk_mul_f32 v[166:167], v[154:155], v[30:31] op_sel_hi:[0,1]
	v_pk_mul_f32 v[164:165], v[154:155], v[28:29] op_sel_hi:[0,1]
	v_lshl_add_u64 v[168:169], v[156:157], 0, s[36:37]
	v_cvt_pk_bf16_f32 v164, v164, v165
	v_cvt_pk_bf16_f32 v165, v166, v167
	v_cvt_pk_bf16_f32 v166, v172, v173
	v_cvt_pk_bf16_f32 v167, v170, v171
	global_store_dwordx4 v[168:169], v[164:167], off offset:256 nt
	v_pk_mul_f32 v[170:171], v[154:155], v[34:35] op_sel_hi:[0,1]
	v_pk_mul_f32 v[172:173], v[154:155], v[32:33] op_sel_hi:[0,1]
	v_pk_mul_f32 v[166:167], v[154:155], v[38:39] op_sel_hi:[0,1]
	v_pk_mul_f32 v[164:165], v[154:155], v[36:37] op_sel_hi:[0,1]
	v_cvt_pk_bf16_f32 v164, v164, v165
	v_cvt_pk_bf16_f32 v165, v166, v167
	v_cvt_pk_bf16_f32 v167, v170, v171
	v_add_co_u32_e32 v170, vcc, s92, v156
	v_cvt_pk_bf16_f32 v166, v172, v173
	s_nop 0
	v_addc_co_u32_e32 v171, vcc, 0, v157, vcc
	v_mov_b64_e32 v[248:249], v[170:171]
	v_mov_b64_e32 v[244:245], v[164:165]
	v_mov_b64_e32 v[246:247], v[166:167]
	v_pk_mul_f32 v[170:171], v[154:155], v[10:11] op_sel_hi:[0,1]
	v_pk_mul_f32 v[172:173], v[154:155], v[8:9] op_sel_hi:[0,1]
	v_pk_mul_f32 v[166:167], v[154:155], v[14:15] op_sel_hi:[0,1]
	v_pk_mul_f32 v[164:165], v[154:155], v[12:13] op_sel_hi:[0,1]
	v_lshl_add_u64 v[168:169], v[156:157], 0, s[38:39]
	v_cvt_pk_bf16_f32 v164, v164, v165
	v_cvt_pk_bf16_f32 v165, v166, v167
	v_cvt_pk_bf16_f32 v166, v172, v173
	v_cvt_pk_bf16_f32 v167, v170, v171
	global_store_dwordx4 v[168:169], v[164:167], off offset:256 nt
	v_lshl_add_u64 v[168:169], v[156:157], 0, s[42:43]
	v_pk_mul_f32 v[170:171], v[154:155], v[18:19] op_sel_hi:[0,1]
	v_pk_mul_f32 v[166:167], v[154:155], v[22:23] op_sel_hi:[0,1]
	v_pk_mul_f32 v[164:165], v[154:155], v[20:21] op_sel_hi:[0,1]
	v_pk_mul_f32 v[172:173], v[154:155], v[16:17] op_sel_hi:[0,1]
	v_add_co_u32_e32 v156, vcc, s93, v156
	v_cvt_pk_bf16_f32 v164, v164, v165
	v_cvt_pk_bf16_f32 v165, v166, v167
	v_cvt_pk_bf16_f32 v166, v172, v173
	v_cvt_pk_bf16_f32 v167, v170, v171
	v_addc_co_u32_e32 v157, vcc, 0, v157, vcc
	v_mov_b64_e32 v[254:255], v[156:157]
	v_mov_b64_e32 v[250:251], v[164:165]
	v_mov_b64_e32 v[252:253], v[166:167]
	v_pk_mul_f32 v[156:157], v[154:155], v[6:7] op_sel_hi:[0,1]
	v_pk_mul_f32 v[170:171], v[154:155], v[0:1] op_sel_hi:[0,1]
	v_pk_mul_f32 v[164:165], v[154:155], v[4:5] op_sel_hi:[0,1]
	v_pk_mul_f32 v[166:167], v[154:155], v[2:3] op_sel_hi:[0,1]
	v_cvt_pk_bf16_f32 v154, v164, v165
	v_cvt_pk_bf16_f32 v155, v156, v157
	v_cvt_pk_bf16_f32 v156, v170, v171
	v_cvt_pk_bf16_f32 v157, v166, v167
	global_store_dwordx4 v[168:169], v[154:157], off offset:256 nt

.LBB0_213:
	s_lshr_b32 s45, s45, 10
	s_add_i32 s47, s94, 0x3fffc
	s_and_b32 s45, s45, 0x3fffc
	v_and_b32_e32 v136, 0xfcf, v152
	s_or_b32 s45, s45, s47
	v_lshl_or_b32 v136, s45, 14, v136
	v_or_b32_e32 v154, s72, v136
	v_cvt_pk_bf16_f32 v68, v68, v69
	v_cvt_pk_bf16_f32 v69, v70, v71
	v_cvt_pk_bf16_f32 v70, v64, v65
	v_or_b32_e32 v64, 0x2030, v154
	v_ashrrev_i32_e32 v65, 31, v64
	v_lshlrev_b64 v[64:65], 7, v[64:65]
	v_cvt_pk_bf16_f32 v71, v66, v67
	v_lshl_add_u64 v[64:65], v[142:143], 0, v[64:65]
	global_store_dwordx4 v[64:65], v[68:71], off nt
	v_add_u32_e32 v64, 0x80, v152
	v_and_b32_e32 v65, 0xfcf, v64
	v_lshrrev_b32_e32 v64, 10, v64
	v_cvt_pk_bf16_f32 v108, v108, v109
	v_cvt_pk_bf16_f32 v109, v110, v111
	v_cvt_pk_bf16_f32 v110, v104, v105
	v_or_b32_e32 v104, 0x2000, v154
	v_cvt_pk_bf16_f32 v92, v92, v93
	v_cvt_pk_bf16_f32 v93, v94, v95
	v_cvt_pk_bf16_f32 v94, v88, v89
	v_or_b32_e32 v88, 0x2010, v154
	v_cvt_pk_bf16_f32 v76, v76, v77
	v_cvt_pk_bf16_f32 v77, v78, v79
	v_cvt_pk_bf16_f32 v78, v72, v73
	v_or_b32_e32 v72, 0x2020, v154
	v_and_b32_e32 v64, 0x3fffc, v64
	v_ashrrev_i32_e32 v105, 31, v104
	v_ashrrev_i32_e32 v89, 31, v88
	v_ashrrev_i32_e32 v73, 31, v72
	v_or_b32_e32 v64, s47, v64
	v_lshlrev_b64 v[104:105], 7, v[104:105]
	v_lshlrev_b64 v[88:89], 7, v[88:89]
	v_lshlrev_b64 v[72:73], 7, v[72:73]
	v_lshlrev_b32_e32 v64, 14, v64
	v_cvt_pk_bf16_f32 v111, v106, v107
	v_lshl_add_u64 v[104:105], v[142:143], 0, v[104:105]
	v_cvt_pk_bf16_f32 v95, v90, v91
	v_lshl_add_u64 v[88:89], v[142:143], 0, v[88:89]
	v_cvt_pk_bf16_f32 v79, v74, v75
	v_lshl_add_u64 v[72:73], v[142:143], 0, v[72:73]
	v_or3_b32 v64, v64, v65, s72
	global_store_dwordx4 v[104:105], v[108:111], off nt
	global_store_dwordx4 v[88:89], v[92:95], off nt
	global_store_dwordx4 v[72:73], v[76:79], off nt
	v_or_b32_e32 v108, 16, v154
	v_or_b32_e32 v92, 32, v154
	v_or_b32_e32 v76, 48, v154
	v_cvt_pk_bf16_f32 v44, v44, v45
	v_cvt_pk_bf16_f32 v45, v46, v47
	v_cvt_pk_bf16_f32 v46, v40, v41
	v_or_b32_e32 v40, 0x2000, v64
	v_cvt_pk_bf16_f32 v28, v28, v29
	v_cvt_pk_bf16_f32 v29, v30, v31
	v_cvt_pk_bf16_f32 v30, v24, v25
	v_or_b32_e32 v24, 0x2010, v64
	v_cvt_pk_bf16_f32 v12, v12, v13
	v_cvt_pk_bf16_f32 v13, v14, v15
	v_cvt_pk_bf16_f32 v14, v8, v9
	v_or_b32_e32 v8, 0x2020, v64
	v_ashrrev_i32_e32 v155, 31, v154
	v_ashrrev_i32_e32 v109, 31, v108
	v_ashrrev_i32_e32 v93, 31, v92
	v_ashrrev_i32_e32 v77, 31, v76
	v_ashrrev_i32_e32 v41, 31, v40
	v_ashrrev_i32_e32 v25, 31, v24
	v_ashrrev_i32_e32 v9, 31, v8
	v_cvt_pk_bf16_f32 v124, v124, v125
	v_cvt_pk_bf16_f32 v125, v126, v127
	v_cvt_pk_bf16_f32 v126, v120, v121
	v_lshlrev_b64 v[120:121], 7, v[154:155]
	v_lshlrev_b64 v[108:109], 7, v[108:109]
	v_lshlrev_b64 v[92:93], 7, v[92:93]
	v_lshlrev_b64 v[76:77], 7, v[76:77]
	v_lshlrev_b64 v[40:41], 7, v[40:41]
	v_lshlrev_b64 v[24:25], 7, v[24:25]
	v_lshlrev_b64 v[8:9], 7, v[8:9]
	v_cvt_pk_bf16_f32 v127, v122, v123
	v_lshl_add_u64 v[120:121], v[142:143], 0, v[120:121]
	v_cvt_pk_bf16_f32 v104, v116, v117
	v_cvt_pk_bf16_f32 v105, v118, v119
	v_cvt_pk_bf16_f32 v106, v112, v113
	v_cvt_pk_bf16_f32 v107, v114, v115
	v_lshl_add_u64 v[108:109], v[142:143], 0, v[108:109]
	v_cvt_pk_bf16_f32 v88, v100, v101
	v_cvt_pk_bf16_f32 v89, v102, v103
	v_cvt_pk_bf16_f32 v90, v96, v97
	v_cvt_pk_bf16_f32 v91, v98, v99
	v_lshl_add_u64 v[92:93], v[142:143], 0, v[92:93]
	v_cvt_pk_bf16_f32 v72, v84, v85
	v_cvt_pk_bf16_f32 v73, v86, v87
	v_cvt_pk_bf16_f32 v74, v80, v81
	v_cvt_pk_bf16_f32 v75, v82, v83
	v_lshl_add_u64 v[76:77], v[142:143], 0, v[76:77]
	v_cvt_pk_bf16_f32 v47, v42, v43
	v_lshl_add_u64 v[40:41], v[142:143], 0, v[40:41]
	v_cvt_pk_bf16_f32 v31, v26, v27
	v_lshl_add_u64 v[24:25], v[142:143], 0, v[24:25]
	v_cvt_pk_bf16_f32 v15, v10, v11
	v_lshl_add_u64 v[8:9], v[142:143], 0, v[8:9]
	global_store_dwordx4 v[120:121], v[124:127], off nt
	global_store_dwordx4 v[108:109], v[104:107], off nt
	global_store_dwordx4 v[92:93], v[88:91], off nt
	global_store_dwordx4 v[76:77], v[72:75], off nt
	global_store_dwordx4 v[40:41], v[44:47], off nt
	global_store_dwordx4 v[24:25], v[28:31], off nt
	global_store_dwordx4 v[8:9], v[12:15], off nt
	v_or_b32_e32 v44, 16, v64
	v_or_b32_e32 v28, 32, v64
	v_or_b32_e32 v12, 48, v64
	v_cvt_pk_bf16_f32 v4, v4, v5
	v_cvt_pk_bf16_f32 v5, v6, v7
	v_cvt_pk_bf16_f32 v6, v0, v1
	v_or_b32_e32 v0, 0x2030, v64
	v_ashrrev_i32_e32 v65, 31, v64
	v_ashrrev_i32_e32 v45, 31, v44
	v_ashrrev_i32_e32 v29, 31, v28
	v_ashrrev_i32_e32 v13, 31, v12
	v_ashrrev_i32_e32 v1, 31, v0
	v_cvt_pk_bf16_f32 v60, v60, v61
	v_cvt_pk_bf16_f32 v61, v62, v63
	v_cvt_pk_bf16_f32 v62, v56, v57
	v_lshlrev_b64 v[56:57], 7, v[64:65]
	v_lshlrev_b64 v[44:45], 7, v[44:45]
	v_lshlrev_b64 v[28:29], 7, v[28:29]
	v_lshlrev_b64 v[12:13], 7, v[12:13]
	v_lshlrev_b64 v[0:1], 7, v[0:1]
	v_cvt_pk_bf16_f32 v63, v58, v59
	v_lshl_add_u64 v[56:57], v[142:143], 0, v[56:57]
	v_cvt_pk_bf16_f32 v40, v52, v53
	v_cvt_pk_bf16_f32 v41, v54, v55
	v_cvt_pk_bf16_f32 v42, v48, v49
	v_cvt_pk_bf16_f32 v43, v50, v51
	v_lshl_add_u64 v[44:45], v[142:143], 0, v[44:45]
	v_cvt_pk_bf16_f32 v24, v36, v37
	v_cvt_pk_bf16_f32 v25, v38, v39
	v_cvt_pk_bf16_f32 v26, v32, v33
	v_cvt_pk_bf16_f32 v27, v34, v35
	v_lshl_add_u64 v[28:29], v[142:143], 0, v[28:29]
	v_cvt_pk_bf16_f32 v8, v20, v21
	v_cvt_pk_bf16_f32 v9, v22, v23
	v_cvt_pk_bf16_f32 v10, v16, v17
	v_cvt_pk_bf16_f32 v11, v18, v19
	v_lshl_add_u64 v[12:13], v[142:143], 0, v[12:13]
	v_cvt_pk_bf16_f32 v7, v2, v3
	v_lshl_add_u64 v[0:1], v[142:143], 0, v[0:1]
	global_store_dwordx4 v[56:57], v[60:63], off nt
	s_mov_b32 s100, 0
	v_mov_b64_e32 v[236:237], v[44:45]
	v_mov_b64_e32 v[232:233], v[40:41]
	v_mov_b64_e32 v[234:235], v[42:43]
	v_mov_b64_e32 v[242:243], v[28:29]
	v_mov_b64_e32 v[238:239], v[24:25]
	v_mov_b64_e32 v[240:241], v[26:27]
	v_mov_b64_e32 v[248:249], v[12:13]
	v_mov_b64_e32 v[244:245], v[8:9]
	v_mov_b64_e32 v[246:247], v[10:11]
	v_mov_b64_e32 v[254:255], v[0:1]
	v_mov_b64_e32 v[250:251], v[4:5]
	v_mov_b64_e32 v[252:253], v[6:7]
	s_andn2_b64 vcc, exec, s[6:7]
	s_mov_b64 s[6:7], -1
	s_cbranch_vccnz .LBB0_184

.LBB0_216:
	s_cmp_lg_u32 s100, 0
	s_cbranch_scc1 .Ldf_noflush
	global_store_dwordx4 v[236:237], v[232:235], off nt
	global_store_dwordx4 v[242:243], v[238:241], off nt
	global_store_dwordx4 v[248:249], v[244:247], off nt
	global_store_dwordx4 v[254:255], v[250:253], off nt
